# counter hand-off also replaces the post-down grid barrier at it==1 (weights are only overwritten after every workgroup's K loops have arrived)
# speedup vs baseline: 1.0085x; 1.0044x over previous
.LBB0_410:
	v_readlane_b32 s58, v254, 19
	v_readlane_b32 s60, v254, 17
	s_andn2_b64 vcc, exec, s[10:11]
	s_mov_b32 s37, 0x400000
	s_mov_b32 s40, 0x800000
	s_mov_b32 s41, 0xc00000
	s_mov_b32 s45, 0x1000000
	s_waitcnt lgkmcnt(0)
	s_mov_b32 s31, 0xefa18f08
	s_mov_b32 s29, 0x41000000
	v_readlane_b32 s59, v254, 20
	v_readlane_b32 s61, v254, 18
	s_cbranch_vccnz .LBB0_464
	s_mov_b64 s[4:5], s[76:77]
	s_getreg_b32 s10, hwreg(HW_REG_XCC_ID, 0, 4)
	s_waitcnt vmcnt(0)
	v_readlane_b32 s6, v254, 1
	v_readlane_b32 s7, v254, 2
	s_waitcnt vmcnt(0)
	s_barrier
	s_and_saveexec_b64 s[0:1], s[6:7]
	s_cbranch_execz .LBB0_463
	s_cmp_eq_u32 s80, 99
	s_cbranch_scc1 .Lcw_full_2
	s_load_dwordx2 s[4:5], s[76:77], 0xc8
	s_mov_b32 s9, 0x400
	s_cmp_eq_u32 s80, 1
	s_cselect_b32 s9, 0x300, s9
	s_cmp_eq_u32 s80, 0
	s_cselect_b32 s9, 0x100, s9
	v_mov_b32_e32 v2, 0x7800
	s_mov_b32 s100, 0
	s_waitcnt lgkmcnt(0)
